# prologue: fold second w_in chunk loads issued before the first chunk's MFMA loop + modulation silu staging with loads in flight
# speedup vs baseline: 1.0020x; 1.0020x over previous
; __device__ __forceinline__ unsigned cvt_pk_bf16(float lo, float hi) { unsigned r; asm volatile("v_cvt_pk_bf16_f32 %0, %1, %2" : "=v"(r) : "v"(lo), "v"(hi)); return r; }
; __device__ __forceinline__ void p0_fold_item(const Params& p, LAS unsigned char* lds, int item) {
;     ...
;     for (int sub = 0; sub < 2; ++sub) { const int i0 = ib + sub * 32;
;     for (int u = tid; u < 4096; u += NTHREADS) { const int il = u >> 7, c = u & 127; wt[il * 129 + c] = p.w_in[(size_t)(i0 + il) * 2048 + g * 128 + c]; }
;     __syncthreads();
;     {
;         const int li = lane & 15, lk = lane >> 4;
;         f32x4 acc0 = (f32x4){0.f, 0.f, 0.f, 0.f}, acc1 = (f32x4){0.f, 0.f, 0.f, 0.f};
; #pragma unroll 4
;         for (int ks = 0; ks < 32; ++ks) { const int c = 4 * ks + lk; const float a = Gm[c * 128 + 16 * w + li], b0 = wt[li * 129 + c], b1 = wt[(16 + li) * 129 + c];
;             acc0 = __builtin_amdgcn_mfma_f32_16x16x4f32(a, b0, acc0, 0, 0, 0); acc1 = __builtin_amdgcn_mfma_f32_16x16x4f32(a, b1, acc1, 0, 0, 0); }
;         bf16_t* WA = (bf16_t*)(p.ws + WS_WA);
; #pragma unroll
;         for (int r = 0; r < 4; ++r) { const int d = 16 * w + lk * 4 + r; bf16_t* rowp = WA + (size_t)(which * 512 + g * 128 + d) * DM + i0;
;             rowp[li] = (bf16_t)(cvt_pk_bf16(acc0[r], 0.f) & 0xffffu); rowp[16 + li] = (bf16_t)(cvt_pk_bf16(acc1[r], 0.f) & 0xffffu); }
;     }
;     __syncthreads();
.LBB0_69:
	s_or_b64 exec, exec, s[12:13]
	s_or_b32 s98, s11, 32
	v_or_b32_e32 v212, s98, v42
	v_or_b32_e32 v213, s98, v43
	v_or_b32_e32 v214, s98, v44
	v_or_b32_e32 v215, s98, v45
	v_or_b32_e32 v216, s98, v46
	v_or_b32_e32 v217, s98, v47
	v_or_b32_e32 v218, s98, v48
	v_lshlrev_b32_e32 v212, 11, v212
	v_lshlrev_b32_e32 v213, 11, v213
	v_lshlrev_b32_e32 v214, 11, v214
	v_lshlrev_b32_e32 v215, 11, v215
	v_lshlrev_b32_e32 v216, 11, v216
	v_lshlrev_b32_e32 v217, 11, v217
	v_lshlrev_b32_e32 v218, 11, v218
	v_or3_b32 v212, v109, v212, s10
	v_or3_b32 v213, v109, v213, s10
	v_or3_b32 v214, v109, v214, s10
	v_or3_b32 v215, v109, v215, s10
	v_or3_b32 v216, v109, v216, s10
	v_or3_b32 v217, v109, v217, s10
	v_or3_b32 v218, v109, v218, s10
	v_lshlrev_b32_e32 v212, 2, v212
	v_lshlrev_b32_e32 v213, 2, v213
	v_lshlrev_b32_e32 v214, 2, v214
	v_lshlrev_b32_e32 v215, 2, v215
	v_lshlrev_b32_e32 v216, 2, v216
	v_lshlrev_b32_e32 v217, 2, v217
	v_lshlrev_b32_e32 v218, 2, v218
	v_add_u32_e32 v219, 0xe00, v170
	v_lshrrev_b32_e32 v219, 7, v219
	v_add_lshl_u32 v219, v219, s98, 11
	v_or3_b32 v219, v109, v219, s10
	v_lshlrev_b32_e32 v219, 2, v219
	global_load_dword v204, v212, s[46:47]
	global_load_dword v205, v213, s[46:47]
	global_load_dword v206, v214, s[46:47]
	global_load_dword v207, v215, s[46:47]
	global_load_dword v208, v216, s[46:47]
	global_load_dword v209, v217, s[46:47]
	global_load_dword v210, v218, s[46:47]
	s_and_saveexec_b64 s[98:99], s[4:5]
	global_load_dword v211, v219, s[46:47]
	s_or_b64 exec, exec, s[98:99]
	v_lshlrev_b32_e32 v0, 9, v115
	v_add3_u32 v16, v0, v113, v112
	v_add_u32_e32 v17, v114, v111
	v_mul_u32_u24_e32 v4, 0x204, v42
	v_mul_u32_u24_e32 v5, 0x204, v43
	v_mul_u32_u24_e32 v6, 0x204, v45
	v_mul_u32_u24_e32 v7, 0x204, v47
	v_mul_u32_u24_e32 v18, 0x204, v48
	s_mov_b32 s12, 32
	v_mov_b32_e32 v8, v17
	v_mov_b32_e32 v9, v16
	v_mov_b32_e32 v33, v32
	v_mov_b32_e32 v34, v32
	v_mov_b32_e32 v35, v32
	v_mov_b32_e32 v0, v32
	v_mov_b32_e32 v1, v32
	v_mov_b32_e32 v2, v32
	v_mov_b32_e32 v3, v32
	s_waitcnt lgkmcnt(0)
	s_barrier
.LBB0_70:
	v_add_u32_e32 v14, 0, v9
	v_add_u32_e32 v15, 0, v8
	s_nop 2
	v_add_u32_e32 v10, 0x10000, v14
	v_add_u32_e32 v11, 0x20000, v15
	v_add_u32_e32 v12, 0x22040, v15
	v_add_u32_e32 v19, 0x20010, v15
	v_add_u32_e32 v20, 0x22050, v15
	v_add_u32_e32 v21, 0x11000, v14
	v_add_u32_e32 v22, 0x20020, v15
	v_add_u32_e32 v13, 0x10800, v14
	ds_read_b32 v10, v10
	ds_read_b32 v11, v11
	ds_read_b32 v12, v12
	ds_read_b32 v23, v13
	ds_read_b32 v19, v19
	ds_read_b32 v20, v20
	ds_read_b32 v21, v21
	ds_read_b32 v22, v22
	s_waitcnt lgkmcnt(6)
	v_mfma_f32_16x16x4_f32 v[0:3], v10, v11, v[0:3]
	v_add_u32_e32 v14, 0x11800, v14
	s_add_i32 s12, s12, -4
	v_add_u32_e32 v9, 0x2000, v9
	s_cmp_eq_u32 s12, 0
	v_add_u32_e32 v8, 64, v8
	s_waitcnt lgkmcnt(5)
	v_mfma_f32_16x16x4_f32 v[10:13], v10, v12, v[32:35]
	s_waitcnt lgkmcnt(3)
	v_mfma_f32_16x16x4_f32 v[0:3], v23, v19, v[0:3]
	v_add_u32_e32 v19, 0x22060, v15
	s_waitcnt lgkmcnt(2)
	v_mfma_f32_16x16x4_f32 v[10:13], v23, v20, v[10:13]
	v_add_u32_e32 v20, 0x20030, v15
	v_add_u32_e32 v15, 0x22070, v15
	ds_read_b32 v19, v19
	ds_read_b32 v14, v14
	ds_read_b32 v20, v20
	ds_read_b32 v15, v15
	s_waitcnt lgkmcnt(4)
	v_mfma_f32_16x16x4_f32 v[0:3], v21, v22, v[0:3]
	s_waitcnt lgkmcnt(3)
	v_mfma_f32_16x16x4_f32 v[10:13], v21, v19, v[10:13]
	s_waitcnt lgkmcnt(1)
	v_mfma_f32_16x16x4_f32 v[0:3], v14, v20, v[0:3]
	s_waitcnt lgkmcnt(0)
	v_mfma_f32_16x16x4_f32 v[32:35], v14, v15, v[10:13]
	s_cbranch_scc0 .LBB0_70
	s_and_b32 s12, s16, 0x200
	v_or3_b32 v8, s12, v110, v111
	s_lshl_b32 s12, s11, 1
	v_mov_b32_e32 v9, 0
	s_add_u32 s12, s8, s12
	s_addc_u32 s13, s9, 0
	v_mov_b32_e32 v41, v9
	v_add_lshl_u32 v8, v8, s10, 11
	v_lshl_add_u64 v[20:21], s[12:13], 0, v[40:41]
	v_lshl_add_u64 v[22:23], v[20:21], 0, v[8:9]
	v_cvt_pk_bf16_f32 v0, v0, v9
	v_or_b32_e32 v10, 0x800, v8
	v_mov_b32_e32 v11, v9
	global_store_short v[22:23], v0, off
	v_cvt_pk_bf16_f32 v0, v32, v9
	v_lshl_add_u64 v[24:25], v[20:21], 0, v[10:11]
	global_store_short v[22:23], v0, off offset:32
	v_cvt_pk_bf16_f32 v0, v1, v9
	v_or_b32_e32 v12, 0x1000, v8
	v_mov_b32_e32 v13, v9
	global_store_short v[24:25], v0, off
	v_cvt_pk_bf16_f32 v0, v33, v9
	v_lshl_add_u64 v[26:27], v[20:21], 0, v[12:13]
	global_store_short v[24:25], v0, off offset:32
	v_cvt_pk_bf16_f32 v0, v2, v9
	v_or_b32_e32 v14, 0x1800, v8
	v_mov_b32_e32 v15, v9
	global_store_short v[26:27], v0, off
	v_cvt_pk_bf16_f32 v0, v34, v9
	v_lshl_add_u64 v[20:21], v[20:21], 0, v[14:15]
	global_store_short v[26:27], v0, off offset:32
	v_cvt_pk_bf16_f32 v0, v3, v9
	s_or_b32 s11, s11, 32
	global_store_short v[20:21], v0, off
	v_cvt_pk_bf16_f32 v0, v35, v9
	global_store_short v[20:21], v0, off offset:32
	v_or_b32_e32 v0, s11, v42
	v_lshlrev_b32_e32 v0, 11, v0
	v_or_b32_e32 v1, s11, v43
	v_or_b32_e32 v2, s11, v44
	v_or_b32_e32 v3, s11, v45
	v_or_b32_e32 v19, s11, v46
	v_or_b32_e32 v20, s11, v47
	v_or_b32_e32 v21, s11, v48
	v_or3_b32 v0, v109, v0, s10
	v_lshlrev_b32_e32 v1, 11, v1
	v_lshlrev_b32_e32 v2, 11, v2
	v_lshlrev_b32_e32 v3, 11, v3
	v_lshlrev_b32_e32 v19, 11, v19
	v_lshlrev_b32_e32 v20, 11, v20
	v_lshlrev_b32_e32 v21, 11, v21
	v_lshlrev_b32_e32 v0, 2, v0
	v_or3_b32 v1, v109, v1, s10
	v_or3_b32 v2, v109, v2, s10
	v_or3_b32 v3, v109, v3, s10
	v_or3_b32 v19, v109, v19, s10
	v_or3_b32 v20, v109, v20, s10
	v_or3_b32 v21, v109, v21, s10
	s_barrier
	v_lshlrev_b32_e32 v1, 2, v1
	v_lshlrev_b32_e32 v2, 2, v2
	v_lshlrev_b32_e32 v3, 2, v3
	v_lshlrev_b32_e32 v19, 2, v19
	v_lshlrev_b32_e32 v20, 2, v20
	v_lshlrev_b32_e32 v21, 2, v21
	s_mov_b32 s14, 32
	v_add_u32_e32 v0, v108, v4
	v_add_u32_e32 v1, v108, v5
	v_add_u32_e32 v2, v108, v6
	v_add_u32_e32 v3, v108, v7
	v_add_u32_e32 v4, v108, v18
	s_waitcnt vmcnt(8)
	ds_write_b32 v0, v204
	ds_write_b32 v1, v205
	ds_write_b32 v0, v206 offset:4128
	ds_write_b32 v2, v207
	ds_write_b32 v0, v208 offset:8256
	ds_write_b32 v3, v209
	ds_write_b32 v4, v210
	s_and_saveexec_b64 s[12:13], s[4:5]
	s_cbranch_execz .LBB0_73
	v_add_u32_e32 v0, 0xe00, v170
	v_lshrrev_b32_e32 v2, 7, v0
	s_movk_i32 s4, 0x204
	v_mad_u32_u24 v1, v2, s4, v108
	ds_write_b32 v1, v211
